# all mixer outputs (sg, pool, attention) stored as dwords via DPP lane pairing instead of 2-byte stores; LDS-DMA pool weight staging; on the non-GEMM latency stack
# speedup vs baseline: 1.0038x; 1.0038x over previous
; #define LAS __attribute__((address_space(3)))
; __device__ __forceinline__ void pool_item(int l, int it, LAS unsigned char* lds, const bf16_t* PLB, bf16_t* YC, const float* pool_w, const float* pool_scale, int tid, int lane, int wave) {
;     ...
;         const int g = wave & 3, tt = wave >> 2, q = lane & 31, hi = lane >> 5;
;         f32x16 acc0 = {}, acc1 = {};
; #pragma unroll
;         for (int ks = 0; ks < 4; ++ks) {
;             const bf16x8 Af = *(const LAS bf16x8*)(pl + (tt * 32 + q) * PS + g * 64 + 16 * ks + 8 * hi);
;             const bf16x8 B0 = *(const LAS bf16x8*)(wT + (g * 64 + q) * WS_ + 16 * ks + 8 * hi), B1 = *(const LAS bf16x8*)(wT + (g * 64 + 32 + q) * WS_ + 16 * ks + 8 * hi);
;             acc0 = __builtin_amdgcn_mfma_f32_32x32x16_bf16(Af, B0, acc0, 0, 0, 0);
;             acc1 = __builtin_amdgcn_mfma_f32_32x32x16_bf16(Af, B1, acc1, 0, 0, 0);
;         }
;         const float sc0 = pool_scale[l * BW + g * 64 + q], sc1 = pool_scale[l * BW + g * 64 + 32 + q];
;         bf16_t* orow = YC + (size_t)2 * MTOK * BW + (r0 + tt * 32 + 4 * hi) * BW + g * 64 + q;
.LBB0_86:
	s_waitcnt lgkmcnt(0)
	s_barrier
	ds_read_b128 v[16:19], v42
	ds_read_b128 v[0:3], v44
	ds_read_b128 v[46:49], v42 offset:32
	ds_read_b128 v[50:53], v44 offset:32
	s_waitcnt lgkmcnt(2)
	v_mfma_f32_32x32x16_bf16 v[0:15], v[16:19], v[0:3], 0
	ds_read_b128 v[20:23], v45
	ds_read_b128 v[54:57], v45 offset:32
	s_movk_i32 s0, 0xd000
	s_add_i32 s2, s2, s96
	s_waitcnt lgkmcnt(1)
	v_mfma_f32_32x32x16_bf16 v[16:31], v[16:19], v[20:23], 0
	v_mfma_f32_32x32x16_bf16 v[0:15], v[46:49], v[50:53], v[0:15]
	s_waitcnt lgkmcnt(0)
	v_mfma_f32_32x32x16_bf16 v[16:31], v[46:49], v[54:57], v[16:31]
	ds_read_b128 v[46:49], v42 offset:64
	ds_read_b128 v[50:53], v44 offset:64
	ds_read_b128 v[54:57], v42 offset:96
	ds_read_b128 v[58:61], v44 offset:96
	s_waitcnt lgkmcnt(2)
	v_mfma_f32_32x32x16_bf16 v[0:15], v[46:49], v[50:53], v[0:15]
	ds_read_b128 v[50:53], v45 offset:64
	ds_read_b128 v[62:65], v45 offset:96
	s_waitcnt lgkmcnt(1)
	v_mfma_f32_32x32x16_bf16 v[16:31], v[46:49], v[50:53], v[16:31]
	global_load_dword v52, v[36:37], off
	global_load_dword v53, v[38:39], off
	v_add_co_u32_e32 v46, vcc, s0, v40
	s_movk_i32 s0, 0xe000
	s_nop 0
	v_addc_co_u32_e32 v47, vcc, -1, v41, vcc
	v_add_co_u32_e32 v48, vcc, s0, v40
	v_mfma_f32_32x32x16_bf16 v[0:15], v[54:57], v[58:61], v[0:15]
	s_nop 0
	v_addc_co_u32_e32 v49, vcc, -1, v41, vcc
	s_movk_i32 s0, 0xf000
	v_add_co_u32_e32 v50, vcc, s0, v40
	v_readlane_b32 s0, v253, 45
	s_nop 0
	v_addc_co_u32_e32 v51, vcc, -1, v41, vcc
	s_waitcnt lgkmcnt(0)
	v_mfma_f32_32x32x16_bf16 v[16:31], v[54:57], v[62:65], v[16:31]
	s_add_i32 s3, s3, s0
	v_readlane_b32 s0, v253, 48
	v_readlane_b32 s1, v253, 49
	s_add_u32 s20, s20, s0
	s_addc_u32 s21, s21, s1
	v_readlane_b32 s0, v253, 43
	v_readlane_b32 s1, v253, 44
	s_cmpk_gt_i32 s2, 0x1ff
	s_waitcnt vmcnt(0)
; __device__ __forceinline__ bf16_t f2bf(float f) { return (bf16_t)(cvt_pk_bf16(f, f) & 0xffffu); }
; __device__ __forceinline__ void pool_item(int l, int it, LAS unsigned char* lds, const bf16_t* PLB, bf16_t* YC, const float* pool_w, const float* pool_scale, int tid, int lane, int wave) {
;     ...
;         const float sc0 = pool_scale[l * BW + g * 64 + q], sc1 = pool_scale[l * BW + g * 64 + 32 + q];
;         bf16_t* orow = YC + (size_t)2 * MTOK * BW + (r0 + tt * 32 + 4 * hi) * BW + g * 64 + q;
; #pragma unroll
;         for (int r = 0; r < 16; ++r) {
;             orow[0] = f2bf(acc0[r] * sc0); orow[32] = f2bf(acc1[r] * sc1);
;             orow += ((r & 3) == 3 ? 5 : 1) * BW;
;         }
	s_nop 0
	v_mul_f32_e32 v0, v0, v52
	v_mul_f32_e32 v1, v1, v52
	v_mul_f32_e32 v2, v2, v52
	v_mul_f32_e32 v3, v3, v52
	v_mul_f32_e32 v4, v4, v52
	v_mul_f32_e32 v5, v5, v52
	v_mul_f32_e32 v6, v6, v52
	v_mul_f32_e32 v7, v7, v52
	v_mul_f32_e32 v8, v8, v52
	v_mul_f32_e32 v9, v9, v52
	v_mul_f32_e32 v10, v10, v52
	v_mul_f32_e32 v11, v11, v52
	v_mul_f32_e32 v12, v12, v52
	v_mul_f32_e32 v13, v13, v52
	v_mul_f32_e32 v14, v14, v52
	v_mul_f32_e32 v15, v15, v52
	v_mul_f32_e32 v16, v16, v53
	v_mul_f32_e32 v17, v17, v53
	v_mul_f32_e32 v18, v18, v53
	v_mul_f32_e32 v19, v19, v53
	v_mul_f32_e32 v20, v20, v53
	v_mul_f32_e32 v21, v21, v53
	v_mul_f32_e32 v22, v22, v53
	v_mul_f32_e32 v23, v23, v53
	v_mul_f32_e32 v24, v24, v53
	v_mul_f32_e32 v25, v25, v53
	v_mul_f32_e32 v26, v26, v53
	v_mul_f32_e32 v27, v27, v53
	v_mul_f32_e32 v28, v28, v53
	v_mul_f32_e32 v29, v29, v53
	v_mul_f32_e32 v30, v30, v53
	v_mul_f32_e32 v31, v31, v53
	v_and_b32_e32 v54, 1, v244
	v_mul_u32_u24_e32 v54, 0x1fe, v54
	v_mov_b32_e32 v55, 0
	s_mov_b32 s94, 0xaaaaaaaa
	s_mov_b32 s95, 0xaaaaaaaa
	v_lshl_add_u64 v[56:57], v[46:47], 0, v[54:55]
	v_mov_b32_dpp v58, v0 quad_perm:[1,0,3,2] row_mask:0xf bank_mask:0xf
	v_mov_b32_dpp v59, v1 quad_perm:[1,0,3,2] row_mask:0xf bank_mask:0xf
	v_cndmask_b32_e64 v59, v0, v59, s[94:95]
	v_cndmask_b32_e64 v58, v58, v1, s[94:95]
	v_cvt_pk_bf16_f32 v58, v59, v58
	global_store_dword v[56:57], v58, off offset:-1600
	v_mov_b32_dpp v58, v16 quad_perm:[1,0,3,2] row_mask:0xf bank_mask:0xf
	v_mov_b32_dpp v59, v17 quad_perm:[1,0,3,2] row_mask:0xf bank_mask:0xf
	v_cndmask_b32_e64 v59, v16, v59, s[94:95]
	v_cndmask_b32_e64 v58, v58, v17, s[94:95]
	v_cvt_pk_bf16_f32 v58, v59, v58
	global_store_dword v[56:57], v58, off offset:-1536
	v_mov_b32_dpp v58, v2 quad_perm:[1,0,3,2] row_mask:0xf bank_mask:0xf
	v_mov_b32_dpp v59, v3 quad_perm:[1,0,3,2] row_mask:0xf bank_mask:0xf
	v_cndmask_b32_e64 v59, v2, v59, s[94:95]
	v_cndmask_b32_e64 v58, v58, v3, s[94:95]
	v_cvt_pk_bf16_f32 v58, v59, v58
	global_store_dword v[56:57], v58, off offset:-576
	v_mov_b32_dpp v58, v18 quad_perm:[1,0,3,2] row_mask:0xf bank_mask:0xf
	v_mov_b32_dpp v59, v19 quad_perm:[1,0,3,2] row_mask:0xf bank_mask:0xf
	v_cndmask_b32_e64 v59, v18, v59, s[94:95]
	v_cndmask_b32_e64 v58, v58, v19, s[94:95]
	v_cvt_pk_bf16_f32 v58, v59, v58
	global_store_dword v[56:57], v58, off offset:-512
	v_lshl_add_u64 v[56:57], v[48:49], 0, v[54:55]
	v_mov_b32_dpp v58, v4 quad_perm:[1,0,3,2] row_mask:0xf bank_mask:0xf
	v_mov_b32_dpp v59, v5 quad_perm:[1,0,3,2] row_mask:0xf bank_mask:0xf
	v_cndmask_b32_e64 v59, v4, v59, s[94:95]
	v_cndmask_b32_e64 v58, v58, v5, s[94:95]
	v_cvt_pk_bf16_f32 v58, v59, v58
	global_store_dword v[56:57], v58, off offset:-1600
	v_mov_b32_dpp v58, v20 quad_perm:[1,0,3,2] row_mask:0xf bank_mask:0xf
	v_mov_b32_dpp v59, v21 quad_perm:[1,0,3,2] row_mask:0xf bank_mask:0xf
	v_cndmask_b32_e64 v59, v20, v59, s[94:95]
	v_cndmask_b32_e64 v58, v58, v21, s[94:95]
	v_cvt_pk_bf16_f32 v58, v59, v58
	global_store_dword v[56:57], v58, off offset:-1536
	v_mov_b32_dpp v58, v6 quad_perm:[1,0,3,2] row_mask:0xf bank_mask:0xf
	v_mov_b32_dpp v59, v7 quad_perm:[1,0,3,2] row_mask:0xf bank_mask:0xf
	v_cndmask_b32_e64 v59, v6, v59, s[94:95]
	v_cndmask_b32_e64 v58, v58, v7, s[94:95]
	v_cvt_pk_bf16_f32 v58, v59, v58
	global_store_dword v[56:57], v58, off offset:-576
	v_mov_b32_dpp v58, v22 quad_perm:[1,0,3,2] row_mask:0xf bank_mask:0xf
	v_mov_b32_dpp v59, v23 quad_perm:[1,0,3,2] row_mask:0xf bank_mask:0xf
	v_cndmask_b32_e64 v59, v22, v59, s[94:95]
	v_cndmask_b32_e64 v58, v58, v23, s[94:95]
	v_cvt_pk_bf16_f32 v58, v59, v58
	global_store_dword v[56:57], v58, off offset:-512
	v_lshl_add_u64 v[56:57], v[50:51], 0, v[54:55]
	v_mov_b32_dpp v58, v8 quad_perm:[1,0,3,2] row_mask:0xf bank_mask:0xf
	v_mov_b32_dpp v59, v9 quad_perm:[1,0,3,2] row_mask:0xf bank_mask:0xf
	v_cndmask_b32_e64 v59, v8, v59, s[94:95]
	v_cndmask_b32_e64 v58, v58, v9, s[94:95]
	v_cvt_pk_bf16_f32 v58, v59, v58
	global_store_dword v[56:57], v58, off offset:-1600
	v_mov_b32_dpp v58, v24 quad_perm:[1,0,3,2] row_mask:0xf bank_mask:0xf
	v_mov_b32_dpp v59, v25 quad_perm:[1,0,3,2] row_mask:0xf bank_mask:0xf
	v_cndmask_b32_e64 v59, v24, v59, s[94:95]
	v_cndmask_b32_e64 v58, v58, v25, s[94:95]
	v_cvt_pk_bf16_f32 v58, v59, v58
	global_store_dword v[56:57], v58, off offset:-1536
	v_mov_b32_dpp v58, v10 quad_perm:[1,0,3,2] row_mask:0xf bank_mask:0xf
	v_mov_b32_dpp v59, v11 quad_perm:[1,0,3,2] row_mask:0xf bank_mask:0xf
	v_cndmask_b32_e64 v59, v10, v59, s[94:95]
	v_cndmask_b32_e64 v58, v58, v11, s[94:95]
	v_cvt_pk_bf16_f32 v58, v59, v58
	global_store_dword v[56:57], v58, off offset:-576
	v_mov_b32_dpp v58, v26 quad_perm:[1,0,3,2] row_mask:0xf bank_mask:0xf
	v_mov_b32_dpp v59, v27 quad_perm:[1,0,3,2] row_mask:0xf bank_mask:0xf
	v_cndmask_b32_e64 v59, v26, v59, s[94:95]
	v_cndmask_b32_e64 v58, v58, v27, s[94:95]
	v_cvt_pk_bf16_f32 v58, v59, v58
	global_store_dword v[56:57], v58, off offset:-512
	v_lshl_add_u64 v[56:57], v[40:41], 0, v[54:55]
	v_mov_b32_dpp v58, v12 quad_perm:[1,0,3,2] row_mask:0xf bank_mask:0xf
	v_mov_b32_dpp v59, v13 quad_perm:[1,0,3,2] row_mask:0xf bank_mask:0xf
	v_cndmask_b32_e64 v59, v12, v59, s[94:95]
	v_cndmask_b32_e64 v58, v58, v13, s[94:95]
	v_cvt_pk_bf16_f32 v58, v59, v58
	global_store_dword v[56:57], v58, off offset:-1600
	v_mov_b32_dpp v58, v28 quad_perm:[1,0,3,2] row_mask:0xf bank_mask:0xf
	v_mov_b32_dpp v59, v29 quad_perm:[1,0,3,2] row_mask:0xf bank_mask:0xf
	v_cndmask_b32_e64 v59, v28, v59, s[94:95]
	v_cndmask_b32_e64 v58, v58, v29, s[94:95]
	v_cvt_pk_bf16_f32 v58, v59, v58
	global_store_dword v[56:57], v58, off offset:-1536
	v_mov_b32_dpp v58, v14 quad_perm:[1,0,3,2] row_mask:0xf bank_mask:0xf
	v_mov_b32_dpp v59, v15 quad_perm:[1,0,3,2] row_mask:0xf bank_mask:0xf
	v_cndmask_b32_e64 v59, v14, v59, s[94:95]
	v_cndmask_b32_e64 v58, v58, v15, s[94:95]
	v_cvt_pk_bf16_f32 v58, v59, v58
	global_store_dword v[56:57], v58, off offset:-576
	v_mov_b32_dpp v58, v30 quad_perm:[1,0,3,2] row_mask:0xf bank_mask:0xf
	v_mov_b32_dpp v59, v31 quad_perm:[1,0,3,2] row_mask:0xf bank_mask:0xf
	v_cndmask_b32_e64 v59, v30, v59, s[94:95]
	v_cndmask_b32_e64 v58, v58, v31, s[94:95]
	v_cvt_pk_bf16_f32 v58, v59, v58
	global_store_dword v[56:57], v58, off offset:-512
	v_lshl_add_u64 v[40:41], v[40:41], 0, s[0:1]
	s_barrier
	s_cbranch_scc1 .LBB0_99

; __device__ __forceinline__ bf16_t f2bf(float f) { return (bf16_t)(cvt_pk_bf16(f, f) & 0xffffu); }
; __device__ __forceinline__ int crow(int r, int hi) { return (r & 3) + 8 * (r >> 2) + 4 * hi; }
; __device__ __forceinline__ void attn_item(int item, const bf16_t* QB, const bf16_t* KB, const bf16_t* VT, bf16_t* YC, int lane) {
;     ...
; #pragma unroll
;     for (int r = 0; r < 16; ++r) {
;         bf16_t* orow = YC + (rowbase + t0 + crow(r, hi)) * BW + h * 64 + q;
;         orow[0] = f2bf(o0[r]); orow[32] = f2bf(o1[r]);
;     }
.LBB0_106:
	v_or_b32_e32 v34, s47, v160
	s_mov_b32 s41, s77
	v_or_b32_e32 v34, s2, v34
	v_mov_b32_e32 v35, s3
	v_lshl_add_u64 v[32:33], v[166:167], 0, s[40:41]
	v_and_b32_e32 v43, 1, v244
	v_sub_u32_e32 v39, 0, v43
	v_lshlrev_b32_e32 v38, 1, v39
	v_lshl_add_u64 v[40:41], v[32:33], 0, v[38:39]
	v_add_u32_e32 v42, v34, v43
	v_mov_b32_e32 v37, s3
	s_mov_b32 s94, 0xaaaaaaaa
	s_mov_b32 s95, 0xaaaaaaaa
	s_nop 3
	v_add_u32_e32 v36, 0, v42
	v_lshlrev_b64 v[44:45], 9, v[36:37]
	v_lshl_add_u64 v[44:45], v[40:41], 0, v[44:45]
	v_mov_b32_dpp v46, v0 quad_perm:[1,0,3,2] row_mask:0xf bank_mask:0xf
	v_mov_b32_dpp v47, v1 quad_perm:[1,0,3,2] row_mask:0xf bank_mask:0xf
	v_cndmask_b32_e64 v47, v0, v47, s[94:95]
	v_cndmask_b32_e64 v46, v46, v1, s[94:95]
	v_cvt_pk_bf16_f32 v46, v47, v46
	global_store_dword v[44:45], v46, off
	v_mov_b32_dpp v46, v16 quad_perm:[1,0,3,2] row_mask:0xf bank_mask:0xf
	v_mov_b32_dpp v47, v17 quad_perm:[1,0,3,2] row_mask:0xf bank_mask:0xf
	v_cndmask_b32_e64 v47, v16, v47, s[94:95]
	v_cndmask_b32_e64 v46, v46, v17, s[94:95]
	v_cvt_pk_bf16_f32 v46, v47, v46
	global_store_dword v[44:45], v46, off offset:64
	v_add_u32_e32 v36, 2, v42
	v_lshlrev_b64 v[44:45], 9, v[36:37]
	v_lshl_add_u64 v[44:45], v[40:41], 0, v[44:45]
	v_mov_b32_dpp v46, v2 quad_perm:[1,0,3,2] row_mask:0xf bank_mask:0xf
	v_mov_b32_dpp v47, v3 quad_perm:[1,0,3,2] row_mask:0xf bank_mask:0xf
	v_cndmask_b32_e64 v47, v2, v47, s[94:95]
	v_cndmask_b32_e64 v46, v46, v3, s[94:95]
	v_cvt_pk_bf16_f32 v46, v47, v46
	global_store_dword v[44:45], v46, off
	v_mov_b32_dpp v46, v18 quad_perm:[1,0,3,2] row_mask:0xf bank_mask:0xf
	v_mov_b32_dpp v47, v19 quad_perm:[1,0,3,2] row_mask:0xf bank_mask:0xf
	v_cndmask_b32_e64 v47, v18, v47, s[94:95]
	v_cndmask_b32_e64 v46, v46, v19, s[94:95]
	v_cvt_pk_bf16_f32 v46, v47, v46
	global_store_dword v[44:45], v46, off offset:64
	v_add_u32_e32 v36, 8, v42
	v_lshlrev_b64 v[44:45], 9, v[36:37]
	v_lshl_add_u64 v[44:45], v[40:41], 0, v[44:45]
	v_mov_b32_dpp v46, v4 quad_perm:[1,0,3,2] row_mask:0xf bank_mask:0xf
	v_mov_b32_dpp v47, v5 quad_perm:[1,0,3,2] row_mask:0xf bank_mask:0xf
	v_cndmask_b32_e64 v47, v4, v47, s[94:95]
	v_cndmask_b32_e64 v46, v46, v5, s[94:95]
	v_cvt_pk_bf16_f32 v46, v47, v46
	global_store_dword v[44:45], v46, off
	v_mov_b32_dpp v46, v20 quad_perm:[1,0,3,2] row_mask:0xf bank_mask:0xf
	v_mov_b32_dpp v47, v21 quad_perm:[1,0,3,2] row_mask:0xf bank_mask:0xf
	v_cndmask_b32_e64 v47, v20, v47, s[94:95]
	v_cndmask_b32_e64 v46, v46, v21, s[94:95]
	v_cvt_pk_bf16_f32 v46, v47, v46
	global_store_dword v[44:45], v46, off offset:64
	v_add_u32_e32 v36, 10, v42
	v_lshlrev_b64 v[44:45], 9, v[36:37]
	v_lshl_add_u64 v[44:45], v[40:41], 0, v[44:45]
	v_mov_b32_dpp v46, v6 quad_perm:[1,0,3,2] row_mask:0xf bank_mask:0xf
	v_mov_b32_dpp v47, v7 quad_perm:[1,0,3,2] row_mask:0xf bank_mask:0xf
	v_cndmask_b32_e64 v47, v6, v47, s[94:95]
	v_cndmask_b32_e64 v46, v46, v7, s[94:95]
	v_cvt_pk_bf16_f32 v46, v47, v46
	global_store_dword v[44:45], v46, off
	v_mov_b32_dpp v46, v22 quad_perm:[1,0,3,2] row_mask:0xf bank_mask:0xf
	v_mov_b32_dpp v47, v23 quad_perm:[1,0,3,2] row_mask:0xf bank_mask:0xf
	v_cndmask_b32_e64 v47, v22, v47, s[94:95]
	v_cndmask_b32_e64 v46, v46, v23, s[94:95]
	v_cvt_pk_bf16_f32 v46, v47, v46
	global_store_dword v[44:45], v46, off offset:64
	v_add_u32_e32 v36, 16, v42
	v_lshlrev_b64 v[44:45], 9, v[36:37]
	v_lshl_add_u64 v[44:45], v[40:41], 0, v[44:45]
	v_mov_b32_dpp v46, v8 quad_perm:[1,0,3,2] row_mask:0xf bank_mask:0xf
	v_mov_b32_dpp v47, v9 quad_perm:[1,0,3,2] row_mask:0xf bank_mask:0xf
	v_cndmask_b32_e64 v47, v8, v47, s[94:95]
	v_cndmask_b32_e64 v46, v46, v9, s[94:95]
	v_cvt_pk_bf16_f32 v46, v47, v46
	global_store_dword v[44:45], v46, off
	v_mov_b32_dpp v46, v24 quad_perm:[1,0,3,2] row_mask:0xf bank_mask:0xf
	v_mov_b32_dpp v47, v25 quad_perm:[1,0,3,2] row_mask:0xf bank_mask:0xf
	v_cndmask_b32_e64 v47, v24, v47, s[94:95]
	v_cndmask_b32_e64 v46, v46, v25, s[94:95]
	v_cvt_pk_bf16_f32 v46, v47, v46
	global_store_dword v[44:45], v46, off offset:64
	v_add_u32_e32 v36, 18, v42
	v_lshlrev_b64 v[44:45], 9, v[36:37]
	v_lshl_add_u64 v[44:45], v[40:41], 0, v[44:45]
	v_mov_b32_dpp v46, v10 quad_perm:[1,0,3,2] row_mask:0xf bank_mask:0xf
	v_mov_b32_dpp v47, v11 quad_perm:[1,0,3,2] row_mask:0xf bank_mask:0xf
	v_cndmask_b32_e64 v47, v10, v47, s[94:95]
	v_cndmask_b32_e64 v46, v46, v11, s[94:95]
	v_cvt_pk_bf16_f32 v46, v47, v46
	global_store_dword v[44:45], v46, off
	v_mov_b32_dpp v46, v26 quad_perm:[1,0,3,2] row_mask:0xf bank_mask:0xf
	v_mov_b32_dpp v47, v27 quad_perm:[1,0,3,2] row_mask:0xf bank_mask:0xf
	v_cndmask_b32_e64 v47, v26, v47, s[94:95]
	v_cndmask_b32_e64 v46, v46, v27, s[94:95]
	v_cvt_pk_bf16_f32 v46, v47, v46
	global_store_dword v[44:45], v46, off offset:64
	v_add_u32_e32 v36, 24, v42
	v_lshlrev_b64 v[44:45], 9, v[36:37]
	v_lshl_add_u64 v[44:45], v[40:41], 0, v[44:45]
	v_mov_b32_dpp v46, v12 quad_perm:[1,0,3,2] row_mask:0xf bank_mask:0xf
	v_mov_b32_dpp v47, v13 quad_perm:[1,0,3,2] row_mask:0xf bank_mask:0xf
	v_cndmask_b32_e64 v47, v12, v47, s[94:95]
	v_cndmask_b32_e64 v46, v46, v13, s[94:95]
	v_cvt_pk_bf16_f32 v46, v47, v46
	global_store_dword v[44:45], v46, off
	v_mov_b32_dpp v46, v28 quad_perm:[1,0,3,2] row_mask:0xf bank_mask:0xf
	v_mov_b32_dpp v47, v29 quad_perm:[1,0,3,2] row_mask:0xf bank_mask:0xf
	v_cndmask_b32_e64 v47, v28, v47, s[94:95]
	v_cndmask_b32_e64 v46, v46, v29, s[94:95]
	v_cvt_pk_bf16_f32 v46, v47, v46
	global_store_dword v[44:45], v46, off offset:64
	v_add_u32_e32 v36, 26, v42
	v_lshlrev_b64 v[44:45], 9, v[36:37]
	v_lshl_add_u64 v[44:45], v[40:41], 0, v[44:45]
	v_mov_b32_dpp v46, v14 quad_perm:[1,0,3,2] row_mask:0xf bank_mask:0xf
	v_mov_b32_dpp v47, v15 quad_perm:[1,0,3,2] row_mask:0xf bank_mask:0xf
	v_cndmask_b32_e64 v47, v14, v47, s[94:95]
	v_cndmask_b32_e64 v46, v46, v15, s[94:95]
	v_cvt_pk_bf16_f32 v46, v47, v46
	global_store_dword v[44:45], v46, off
	v_mov_b32_dpp v46, v30 quad_perm:[1,0,3,2] row_mask:0xf bank_mask:0xf
	v_mov_b32_dpp v47, v31 quad_perm:[1,0,3,2] row_mask:0xf bank_mask:0xf
	v_cndmask_b32_e64 v47, v30, v47, s[94:95]
	v_cndmask_b32_e64 v46, v46, v31, s[94:95]
	v_cvt_pk_bf16_f32 v46, v47, v46
	global_store_dword v[44:45], v46, off offset:64
	s_add_i32 s46, s46, s64
	s_cmpk_gt_i32 s46, 0xfff
	s_cbranch_scc1 .LBB0_114
